# GEMM K-loops P2/P4/P6: LDS fragment reads double-buffered (reads of k-step s+1 issued before MFMAs of k-step s)
# speedup vs baseline: 1.0449x; 1.0070x over previous
; #define MFMA(a, b, c) __builtin_amdgcn_mfma_f32_32x32x16_bf16((a), (b), (c), 0, 0, 0)
; #define G_BARRIER() { asm volatile("s_waitcnt vmcnt(0) lgkmcnt(0)" ::: "memory"); __builtin_amdgcn_s_barrier(); asm volatile("" ::: "memory"); }
;     ...
;         for (int kt = 0; kt < nk; ++kt) {
;             if (kt + 1 < nk) { G_DMA(kt + 1, (kt + 1) & 1); }
;             const unsigned char* sa = lds + (kt & 1) * 65536 + (wt * 32 * TB + r) * 128;
;             const unsigned char* sw = lds + (kt & 1) * 65536 + 32768 + (wf * 64 + r) * 128;
; #pragma unroll
;             for (int ks = 0; ks < 4; ++ks) {
;                 bf16x8 wfr[2], afr[TB];
; #pragma unroll
;                 for (int fb = 0; fb < 2; ++fb) wfr[fb] = *(const bf16x8*)(sw + fb * 4096 + koff[ks]);
; #pragma unroll
;                 for (int tb = 0; tb < TB; ++tb) afr[tb] = *(const bf16x8*)(sa + tb * 4096 + koff[ks]);
; #pragma unroll
;                 for (int fb = 0; fb < 2; ++fb)
; #pragma unroll
;                     for (int tb = 0; tb < TB; ++tb) acc[fb][tb] = MFMA(wfr[fb], afr[tb], acc[fb][tb]);
;             }
;             G_BARRIER();
;         }
.LBB0_202:
	s_add_i32 s8, s7, 0x10000
	s_and_b32 s9, s8, 0x10000
	s_add_i32 s9, s23, s9
	s_mov_b32 m0, s9
	s_nop 0
	global_load_lds_dwordx4 v240, s[74:75]
	s_add_i32 m0, s9, 0x8000
	s_nop 0
	global_load_lds_dwordx4 v240, s[76:77]
	s_add_i32 m0, s9, 0x2000
	s_nop 0
	global_load_lds_dwordx4 v241, s[74:75]
	s_add_i32 m0, s9, 0xa000
	s_nop 0
	global_load_lds_dwordx4 v241, s[76:77]
	s_add_i32 m0, s9, 0x4000
	s_nop 0
	global_load_lds_dwordx4 v242, s[74:75]
	s_add_i32 m0, s9, 0xc000
	s_nop 0
	global_load_lds_dwordx4 v242, s[76:77]
	s_add_i32 m0, s9, 0x6000
	s_nop 0
	global_load_lds_dwordx4 v243, s[74:75]
	s_add_i32 m0, s9, 0xe000
	s_and_b32 s7, s7, 0x10000
	s_nop 0
	global_load_lds_dwordx4 v243, s[76:77]
	s_add_u32 s74, s74, 0x80
	s_addc_u32 s75, s75, 0
	s_add_u32 s76, s76, 0x80
	s_addc_u32 s77, s77, 0
	s_add_i32 s7, s7, 16
	v_add3_u32 v132, s7, v183, v154
	v_add3_u32 v155, s7, v184, v154
	v_add_u32_e32 v169, v155, v159
	v_add_u32_e32 v193, v132, v159
	ds_read_b128 v[128:131], v169 offset:32768
	ds_read_b128 v[174:177], v193
	ds_read_b128 v[194:197], v169 offset:36864
	ds_read_b128 v[198:201], v193 offset:4096
	ds_read_b128 v[204:207], v193 offset:8192
	ds_read_b128 v[208:211], v193 offset:12288
	v_add_u32_e32 v169, v155, v161
	v_add_u32_e32 v178, v132, v161
	ds_read_b128 v[212:215], v169 offset:32768
	ds_read_b128 v[216:219], v178
	ds_read_b128 v[220:223], v169 offset:36864
	ds_read_b128 v[224:227], v178 offset:4096
	ds_read_b128 v[228:231], v178 offset:8192
	ds_read_b128 v[232:235], v178 offset:12288
	s_waitcnt lgkmcnt(6)
	v_mfma_f32_32x32x16_bf16 v[112:127], v[128:131], v[174:177], v[112:127]
	s_add_u32 s4, s4, 0x80
	s_addc_u32 s5, s5, 0
	s_cmpk_eq_i32 s4, 0x780
	s_mov_b32 s7, s8
	v_mfma_f32_32x32x16_bf16 v[96:111], v[128:131], v[198:201], v[96:111]
	v_mfma_f32_32x32x16_bf16 v[80:95], v[128:131], v[204:207], v[80:95]
	v_mfma_f32_32x32x16_bf16 v[64:79], v[128:131], v[208:211], v[64:79]
	v_mfma_f32_32x32x16_bf16 v[48:63], v[194:197], v[174:177], v[48:63]
	v_mfma_f32_32x32x16_bf16 v[32:47], v[194:197], v[198:201], v[32:47]
	v_mfma_f32_32x32x16_bf16 v[16:31], v[194:197], v[204:207], v[16:31]
	v_mfma_f32_32x32x16_bf16 v[0:15], v[194:197], v[208:211], v[0:15]
	v_add_u32_e32 v169, v155, v180
	v_add_u32_e32 v178, v132, v180
	ds_read_b128 v[128:131], v169 offset:32768
	ds_read_b128 v[174:177], v178
	ds_read_b128 v[194:197], v169 offset:36864
	ds_read_b128 v[198:201], v178 offset:4096
	ds_read_b128 v[204:207], v178 offset:8192
	ds_read_b128 v[208:211], v178 offset:12288
	s_waitcnt lgkmcnt(6)
	v_mfma_f32_32x32x16_bf16 v[112:127], v[212:215], v[216:219], v[112:127]
	v_mfma_f32_32x32x16_bf16 v[96:111], v[212:215], v[224:227], v[96:111]
	v_mfma_f32_32x32x16_bf16 v[80:95], v[212:215], v[228:231], v[80:95]
	v_mfma_f32_32x32x16_bf16 v[64:79], v[212:215], v[232:235], v[64:79]
	v_mfma_f32_32x32x16_bf16 v[48:63], v[220:223], v[216:219], v[48:63]
	v_mfma_f32_32x32x16_bf16 v[32:47], v[220:223], v[224:227], v[32:47]
	v_mfma_f32_32x32x16_bf16 v[16:31], v[220:223], v[228:231], v[16:31]
	v_mfma_f32_32x32x16_bf16 v[0:15], v[220:223], v[232:235], v[0:15]
	v_add_u32_e32 v155, v155, v181
	v_add_u32_e32 v132, v132, v181
	ds_read_b128 v[212:215], v155 offset:32768
	ds_read_b128 v[216:219], v132
	ds_read_b128 v[220:223], v155 offset:36864
	ds_read_b128 v[224:227], v132 offset:4096
	ds_read_b128 v[228:231], v132 offset:8192
	ds_read_b128 v[232:235], v132 offset:12288
	s_waitcnt lgkmcnt(6)
	v_mfma_f32_32x32x16_bf16 v[112:127], v[128:131], v[174:177], v[112:127]
	v_mfma_f32_32x32x16_bf16 v[96:111], v[128:131], v[198:201], v[96:111]
	v_mfma_f32_32x32x16_bf16 v[80:95], v[128:131], v[204:207], v[80:95]
	v_mfma_f32_32x32x16_bf16 v[64:79], v[128:131], v[208:211], v[64:79]
	v_mfma_f32_32x32x16_bf16 v[48:63], v[194:197], v[174:177], v[48:63]
	v_mfma_f32_32x32x16_bf16 v[32:47], v[194:197], v[198:201], v[32:47]
	v_mfma_f32_32x32x16_bf16 v[16:31], v[194:197], v[204:207], v[16:31]
	v_mfma_f32_32x32x16_bf16 v[0:15], v[194:197], v[208:211], v[0:15]
	s_waitcnt vmcnt(0) lgkmcnt(0)
	s_barrier
	v_mfma_f32_32x32x16_bf16 v[112:127], v[212:215], v[216:219], v[112:127]
	v_mfma_f32_32x32x16_bf16 v[96:111], v[212:215], v[224:227], v[96:111]
	v_mfma_f32_32x32x16_bf16 v[80:95], v[212:215], v[228:231], v[80:95]
	v_mfma_f32_32x32x16_bf16 v[64:79], v[212:215], v[232:235], v[64:79]
	v_mfma_f32_32x32x16_bf16 v[48:63], v[220:223], v[216:219], v[48:63]
	v_mfma_f32_32x32x16_bf16 v[32:47], v[220:223], v[224:227], v[32:47]
	v_mfma_f32_32x32x16_bf16 v[16:31], v[220:223], v[228:231], v[16:31]
	v_mfma_f32_32x32x16_bf16 v[0:15], v[220:223], v[232:235], v[0:15]
	s_cbranch_scc0 .LBB0_202
; #define GAS __attribute__((address_space(1)))
; #define MFMA(a, b, c) __builtin_amdgcn_mfma_f32_32x32x16_bf16((a), (b), (c), 0, 0, 0)
; #define G_BARRIER() { asm volatile("s_waitcnt vmcnt(0) lgkmcnt(0)" ::: "memory"); __builtin_amdgcn_s_barrier(); asm volatile("" ::: "memory"); }
;     ...
;         for (int kt = 0; kt < nk; ++kt) {
;             if (kt + 1 < nk) { G_DMA(kt + 1, (kt + 1) & 1); }
;             const unsigned char* sa = lds + (kt & 1) * 65536 + (wt * 32 * TB + r) * 128;
;             const unsigned char* sw = lds + (kt & 1) * 65536 + 32768 + (wf * 64 + r) * 128;
; #pragma unroll
;             for (int ks = 0; ks < 4; ++ks) {
;                 bf16x8 wfr[2], afr[TB];
; #pragma unroll
;                 for (int fb = 0; fb < 2; ++fb) wfr[fb] = *(const bf16x8*)(sw + fb * 4096 + koff[ks]);
; #pragma unroll
;                 for (int tb = 0; tb < TB; ++tb) afr[tb] = *(const bf16x8*)(sa + tb * 4096 + koff[ks]);
; #pragma unroll
;                 for (int fb = 0; fb < 2; ++fb)
; #pragma unroll
;                     for (int tb = 0; tb < TB; ++tb) acc[fb][tb] = MFMA(wfr[fb], afr[tb], acc[fb][tb]);
;             }
;             G_BARRIER();
;         }
;         const int un = u + nslots;
;         if (un < nloc) {
;             Ag = (const GAS bf16_t*)(A + (size_t)(xcd + nx * (un / Ntiles)) * RM * K) + dsrc; Wg = (const GAS bf16_t*)(Wt + (size_t)(un % Ntiles) * 256 * K) + dsrc;
;             G_DMA(0, 0);
;         }
	v_add_u32_e32 v132, v189, v159
	ds_read_b128 v[128:131], v132
	v_add_u32_e32 v155, v188, v159
	ds_read_b128 v[174:177], v155
	ds_read_b128 v[194:197], v155 offset:4096
	ds_read_b128 v[198:201], v155 offset:8192
	ds_read_b128 v[204:207], v155 offset:12288
	v_add_u32_e32 v155, v188, v161
	s_add_i32 s24, s6, s0
	s_cmp_ge_i32 s24, s1
	s_waitcnt lgkmcnt(0)
	v_mfma_f32_32x32x16_bf16 v[112:127], v[128:131], v[174:177], v[112:127]
	s_cselect_b64 s[96:97], -1, 0
	s_cmp_lt_i32 s24, s1
	v_mfma_f32_32x32x16_bf16 v[96:111], v[128:131], v[194:197], v[96:111]
	v_mfma_f32_32x32x16_bf16 v[80:95], v[128:131], v[198:201], v[80:95]
	v_mfma_f32_32x32x16_bf16 v[64:79], v[128:131], v[204:207], v[64:79]
	ds_read_b128 v[128:131], v132 offset:4096
	v_add_u32_e32 v132, v189, v161
	s_waitcnt lgkmcnt(0)
	v_mfma_f32_32x32x16_bf16 v[48:63], v[128:131], v[174:177], v[48:63]
	ds_read_b128 v[174:177], v155
	v_mfma_f32_32x32x16_bf16 v[32:47], v[128:131], v[194:197], v[32:47]
	ds_read_b128 v[194:197], v155 offset:4096
	v_mfma_f32_32x32x16_bf16 v[16:31], v[128:131], v[198:201], v[16:31]
	ds_read_b128 v[198:201], v155 offset:8192
	v_mfma_f32_32x32x16_bf16 v[0:15], v[128:131], v[204:207], v[0:15]
	ds_read_b128 v[128:131], v132
	ds_read_b128 v[204:207], v155 offset:12288
	v_add_u32_e32 v155, v188, v180
	s_waitcnt lgkmcnt(0)
	v_mfma_f32_32x32x16_bf16 v[112:127], v[128:131], v[174:177], v[112:127]
	v_mfma_f32_32x32x16_bf16 v[96:111], v[128:131], v[194:197], v[96:111]
	v_mfma_f32_32x32x16_bf16 v[80:95], v[128:131], v[198:201], v[80:95]
	v_mfma_f32_32x32x16_bf16 v[64:79], v[128:131], v[204:207], v[64:79]
	ds_read_b128 v[128:131], v132 offset:4096
	v_add_u32_e32 v132, v189, v180
	s_waitcnt lgkmcnt(0)
	v_mfma_f32_32x32x16_bf16 v[48:63], v[128:131], v[174:177], v[48:63]
	ds_read_b128 v[174:177], v155
	v_mfma_f32_32x32x16_bf16 v[32:47], v[128:131], v[194:197], v[32:47]
	ds_read_b128 v[194:197], v155 offset:4096
	v_mfma_f32_32x32x16_bf16 v[16:31], v[128:131], v[198:201], v[16:31]
	ds_read_b128 v[198:201], v155 offset:8192
	v_mfma_f32_32x32x16_bf16 v[0:15], v[128:131], v[204:207], v[0:15]
	ds_read_b128 v[128:131], v132
	ds_read_b128 v[204:207], v155 offset:12288
	v_add_u32_e32 v155, v188, v181
	s_waitcnt lgkmcnt(0)
	v_mfma_f32_32x32x16_bf16 v[112:127], v[128:131], v[174:177], v[112:127]
	v_mfma_f32_32x32x16_bf16 v[96:111], v[128:131], v[194:197], v[96:111]
	v_mfma_f32_32x32x16_bf16 v[80:95], v[128:131], v[198:201], v[80:95]
	v_mfma_f32_32x32x16_bf16 v[64:79], v[128:131], v[204:207], v[64:79]
	ds_read_b128 v[128:131], v132 offset:4096
	v_add_u32_e32 v132, v189, v181
	s_waitcnt lgkmcnt(0)
	v_mfma_f32_32x32x16_bf16 v[48:63], v[128:131], v[174:177], v[48:63]
	ds_read_b128 v[174:177], v155
	v_mfma_f32_32x32x16_bf16 v[32:47], v[128:131], v[194:197], v[32:47]
	ds_read_b128 v[194:197], v155 offset:4096
	v_mfma_f32_32x32x16_bf16 v[16:31], v[128:131], v[198:201], v[16:31]
	ds_read_b128 v[198:201], v155 offset:8192
	v_mfma_f32_32x32x16_bf16 v[0:15], v[128:131], v[204:207], v[0:15]
	ds_read_b128 v[128:131], v132
	ds_read_b128 v[204:207], v155 offset:12288
	s_waitcnt lgkmcnt(0)
	v_mfma_f32_32x32x16_bf16 v[112:127], v[128:131], v[174:177], v[112:127]
	v_mfma_f32_32x32x16_bf16 v[96:111], v[128:131], v[194:197], v[96:111]
	v_mfma_f32_32x32x16_bf16 v[80:95], v[128:131], v[198:201], v[80:95]
	v_mfma_f32_32x32x16_bf16 v[64:79], v[128:131], v[204:207], v[64:79]
	ds_read_b128 v[128:131], v132 offset:4096
	s_waitcnt vmcnt(0) lgkmcnt(0)
	s_barrier
	s_waitcnt lgkmcnt(0)
	v_mfma_f32_32x32x16_bf16 v[48:63], v[128:131], v[174:177], v[48:63]
	v_mfma_f32_32x32x16_bf16 v[32:47], v[128:131], v[194:197], v[32:47]
	v_mfma_f32_32x32x16_bf16 v[16:31], v[128:131], v[198:201], v[16:31]
	v_mfma_f32_32x32x16_bf16 v[0:15], v[128:131], v[204:207], v[0:15]
	s_cbranch_scc0 .LBB0_205
	s_mul_hi_i32 s4, s24, 0x66666667
	s_lshr_b32 s5, s4, 31
	s_ashr_i32 s4, s4, 2
	s_add_i32 s7, s4, s5
	s_lshl_b32 s4, s7, s68
	s_add_i32 s4, s4, s69
	s_ashr_i32 s5, s4, 31
	s_lshl_b64 s[4:5], s[4:5], 19
	s_add_u32 s4, s60, s4
	s_mul_i32 s7, s7, 10
	s_addc_u32 s5, s61, s5
	s_sub_i32 s8, s24, s7
	s_ashr_i32 s9, s8, 31
	s_lshl_b64 s[8:9], s[8:9], 19
	s_mov_b32 m0, s23
	v_mov_b32_e32 v169, v133
	s_add_u32 s8, s62, s8
	v_lshl_add_u64 v[170:171], s[4:5], 0, v[168:169]
	s_addc_u32 s9, s63, s9
	global_load_lds_dwordx4 v168, s[4:5]
	s_add_i32 m0, s23, 0x8000
	v_lshl_add_u64 v[172:173], s[8:9], 0, v[168:169]
	global_load_lds_dwordx4 v168, s[8:9]
	v_lshl_add_u64 v[128:129], v[170:171], 0, s[66:67]
	s_add_i32 m0, s23, 0x2000
	s_nop 0
	global_load_lds_dwordx4 v[128:129], off
	v_lshl_add_u64 v[128:129], v[172:173], 0, s[66:67]
	s_add_i32 m0, s23, 0xa000
	s_nop 0
	global_load_lds_dwordx4 v[128:129], off
	v_lshl_add_u64 v[128:129], v[170:171], 0, s[70:71]
	s_add_i32 m0, s23, 0x4000
	s_nop 0
	global_load_lds_dwordx4 v[128:129], off
	v_lshl_add_u64 v[128:129], v[172:173], 0, s[70:71]
	s_add_i32 m0, s23, 0xc000
	s_nop 0
	global_load_lds_dwordx4 v[128:129], off
	v_lshl_add_u64 v[128:129], v[170:171], 0, s[72:73]
	s_add_i32 m0, s23, 0x6000
	s_nop 0
	global_load_lds_dwordx4 v[128:129], off
	v_lshl_add_u64 v[128:129], v[172:173], 0, s[72:73]
	s_add_i32 m0, s23, 0xe000
	s_nop 0
	global_load_lds_dwordx4 v[128:129], off

; #define GAS __attribute__((address_space(1)))
; #define MFMA(a, b, c) __builtin_amdgcn_mfma_f32_32x32x16_bf16((a), (b), (c), 0, 0, 0)
; #define G_BARRIER() { asm volatile("s_waitcnt vmcnt(0) lgkmcnt(0)" ::: "memory"); __builtin_amdgcn_s_barrier(); asm volatile("" ::: "memory"); }
;     ...
;         for (int kt = 0; kt < nk; ++kt) {
;             if (kt + 1 < nk) { G_DMA(kt + 1, (kt + 1) & 1); }
;             const unsigned char* sa = lds + (kt & 1) * 65536 + (wt * 32 * TB + r) * 128;
;             const unsigned char* sw = lds + (kt & 1) * 65536 + 32768 + (wf * 64 + r) * 128;
; #pragma unroll
;             for (int ks = 0; ks < 4; ++ks) {
;                 bf16x8 wfr[2], afr[TB];
; #pragma unroll
;                 for (int fb = 0; fb < 2; ++fb) wfr[fb] = *(const bf16x8*)(sw + fb * 4096 + koff[ks]);
; #pragma unroll
;                 for (int tb = 0; tb < TB; ++tb) afr[tb] = *(const bf16x8*)(sa + tb * 4096 + koff[ks]);
; #pragma unroll
;                 for (int fb = 0; fb < 2; ++fb)
; #pragma unroll
;                     for (int tb = 0; tb < TB; ++tb) acc[fb][tb] = MFMA(wfr[fb], afr[tb], acc[fb][tb]);
;             }
;             G_BARRIER();
;         }
;         const int un = u + nslots;
;         if (un < nloc) {
;             Ag = (const GAS bf16_t*)(A + (size_t)(xcd + nx * (un / Ntiles)) * RM * K) + dsrc; Wg = (const GAS bf16_t*)(Wt + (size_t)(un % Ntiles) * 256 * K) + dsrc;
;             G_DMA(0, 0);
;         }
.LBB0_482:
	s_add_i32 s7, s6, 0x10000
	s_and_b32 s6, s6, 0x10000
	s_and_b32 s19, s7, 0x10000
	s_add_i32 s6, s6, 16
	s_add_i32 s19, s16, s19
	v_add3_u32 v64, s6, v119, v120
	v_add3_u32 v85, s6, v121, v120
	s_add_i32 s6, s19, 0x8000
	s_mov_b32 m0, s19
	s_nop 0
	global_load_lds_dwordx4 v240, s[76:77]
	s_mov_b32 m0, s6
	s_nop 0
	global_load_lds_dwordx4 v240, s[78:79]
	s_add_i32 m0, s19, 0x2000
	s_mov_b64 s[90:91], 0x40080
	s_nop 0
	global_load_lds_dwordx4 v241, s[76:77]
	s_add_i32 m0, s19, 0xa000
	s_mov_b64 s[92:93], 0x60080
	s_nop 0
	global_load_lds_dwordx4 v241, s[78:79]
	s_add_i32 m0, s19, 0xc000
	s_nop 0
	global_load_lds_dwordx4 v242, s[78:79]
	s_add_i32 m0, s19, 0xe000
	v_add_u32_e32 v102, v85, v114
	s_nop 0
	global_load_lds_dwordx4 v243, s[78:79]
	s_add_u32 s76, s76, 0x80
	s_addc_u32 s77, s77, 0
	s_add_u32 s78, s78, 0x80
	s_addc_u32 s79, s79, 0
	v_add_u32_e32 v103, v64, v114
	ds_read_b128 v[90:93], v102 offset:32768
	ds_read_b128 v[94:97], v103
	ds_read_b128 v[98:101], v103 offset:4096
	ds_read_b128 v[102:105], v102 offset:36864
	v_add_u32_e32 v106, v85, v115
	v_add_u32_e32 v107, v64, v115
	ds_read_b128 v[152:155], v106 offset:32768
	ds_read_b128 v[156:159], v107
	ds_read_b128 v[160:163], v107 offset:4096
	ds_read_b128 v[164:167], v106 offset:36864
	s_waitcnt lgkmcnt(4)
	v_mfma_f32_32x32x16_bf16 v[48:63], v[90:93], v[94:97], v[48:63]
	s_add_u32 s4, s4, 0x80
	s_addc_u32 s5, s5, 0
	s_cmpk_eq_i32 s4, 0x780
	s_mov_b32 s6, s7
	v_mfma_f32_32x32x16_bf16 v[32:47], v[90:93], v[98:101], v[32:47]
	v_mfma_f32_32x32x16_bf16 v[16:31], v[102:105], v[94:97], v[16:31]
	v_mfma_f32_32x32x16_bf16 v[0:15], v[102:105], v[98:101], v[0:15]
	v_add_u32_e32 v106, v85, v116
	v_add_u32_e32 v107, v64, v116
	ds_read_b128 v[90:93], v106 offset:32768
	ds_read_b128 v[94:97], v107
	ds_read_b128 v[98:101], v107 offset:4096
	ds_read_b128 v[102:105], v106 offset:36864
	s_waitcnt lgkmcnt(4)
	v_mfma_f32_32x32x16_bf16 v[48:63], v[152:155], v[156:159], v[48:63]
	v_mfma_f32_32x32x16_bf16 v[32:47], v[152:155], v[160:163], v[32:47]
	v_mfma_f32_32x32x16_bf16 v[16:31], v[164:167], v[156:159], v[16:31]
	v_mfma_f32_32x32x16_bf16 v[0:15], v[164:167], v[160:163], v[0:15]
	v_add_u32_e32 v85, v85, v117
	v_add_u32_e32 v64, v64, v117
	ds_read_b128 v[152:155], v85 offset:32768
	ds_read_b128 v[156:159], v64
	ds_read_b128 v[160:163], v64 offset:4096
	ds_read_b128 v[164:167], v85 offset:36864
	s_waitcnt lgkmcnt(4)
	v_mfma_f32_32x32x16_bf16 v[48:63], v[90:93], v[94:97], v[48:63]
	v_mfma_f32_32x32x16_bf16 v[32:47], v[90:93], v[98:101], v[32:47]
	v_mfma_f32_32x32x16_bf16 v[16:31], v[102:105], v[94:97], v[16:31]
	v_mfma_f32_32x32x16_bf16 v[0:15], v[102:105], v[98:101], v[0:15]
	s_waitcnt vmcnt(0) lgkmcnt(0)
	s_barrier
	v_mfma_f32_32x32x16_bf16 v[48:63], v[152:155], v[156:159], v[48:63]
	v_mfma_f32_32x32x16_bf16 v[32:47], v[152:155], v[160:163], v[32:47]
	v_mfma_f32_32x32x16_bf16 v[16:31], v[164:167], v[156:159], v[16:31]
	v_mfma_f32_32x32x16_bf16 v[0:15], v[164:167], v[160:163], v[0:15]
	s_cbranch_scc0 .LBB0_482
	v_add_u32_e32 v64, v125, v114
	ds_read_b128 v[90:93], v64
	v_add_u32_e32 v85, v124, v114
	ds_read_b128 v[94:97], v85
	ds_read_b128 v[98:101], v85 offset:4096
	ds_read_b128 v[102:105], v64 offset:4096
	v_add_u32_e32 v64, v125, v115
	v_add_u32_e32 v85, v124, v115
	s_waitcnt lgkmcnt(0)
	v_mfma_f32_32x32x16_bf16 v[16:31], v[102:105], v[94:97], v[16:31]
	s_add_i32 s89, s18, s25
	s_cmp_ge_i32 s89, s26
	s_cselect_b64 s[6:7], -1, 0
	s_cmp_lt_i32 s89, s26
	v_mfma_f32_32x32x16_bf16 v[48:63], v[90:93], v[94:97], v[48:63]
	v_mfma_f32_32x32x16_bf16 v[32:47], v[90:93], v[98:101], v[32:47]
	ds_read_b128 v[90:93], v64
	v_mfma_f32_32x32x16_bf16 v[0:15], v[102:105], v[98:101], v[0:15]
	ds_read_b128 v[94:97], v85
	ds_read_b128 v[98:101], v85 offset:4096
	ds_read_b128 v[102:105], v64 offset:4096
	v_add_u32_e32 v64, v125, v116
	v_add_u32_e32 v85, v124, v116
	s_waitcnt lgkmcnt(0)
	v_mfma_f32_32x32x16_bf16 v[48:63], v[90:93], v[94:97], v[48:63]
	v_mfma_f32_32x32x16_bf16 v[32:47], v[90:93], v[98:101], v[32:47]
	ds_read_b128 v[90:93], v64
	v_mfma_f32_32x32x16_bf16 v[16:31], v[102:105], v[94:97], v[16:31]
	v_mfma_f32_32x32x16_bf16 v[0:15], v[102:105], v[98:101], v[0:15]
	ds_read_b128 v[94:97], v85
	ds_read_b128 v[98:101], v85 offset:4096
	ds_read_b128 v[102:105], v64 offset:4096
	v_add_u32_e32 v64, v125, v117
	v_add_u32_e32 v85, v124, v117
	s_waitcnt lgkmcnt(0)
	v_mfma_f32_32x32x16_bf16 v[48:63], v[90:93], v[94:97], v[48:63]
	v_mfma_f32_32x32x16_bf16 v[32:47], v[90:93], v[98:101], v[32:47]
	ds_read_b128 v[90:93], v64
	v_mfma_f32_32x32x16_bf16 v[16:31], v[102:105], v[94:97], v[16:31]
	v_mfma_f32_32x32x16_bf16 v[0:15], v[102:105], v[98:101], v[0:15]
	ds_read_b128 v[94:97], v85
	ds_read_b128 v[98:101], v85 offset:4096
	ds_read_b128 v[102:105], v64 offset:4096
	s_waitcnt vmcnt(0) lgkmcnt(0)
	s_barrier
	s_waitcnt lgkmcnt(0)
	v_mfma_f32_32x32x16_bf16 v[48:63], v[90:93], v[94:97], v[48:63]
	v_mfma_f32_32x32x16_bf16 v[32:47], v[90:93], v[98:101], v[32:47]
	v_mfma_f32_32x32x16_bf16 v[16:31], v[102:105], v[94:97], v[16:31]
	v_mfma_f32_32x32x16_bf16 v[0:15], v[102:105], v[98:101], v[0:15]
	s_cbranch_scc0 .LBB0_485
	s_ashr_i32 s4, s89, 31
	s_lshr_b32 s4, s4, 30
	s_add_i32 s19, s89, s4
	s_ashr_i32 s4, s19, 2
	s_lshl_b32 s4, s4, s22
	s_add_i32 s4, s4, s24
	s_ashr_i32 s5, s4, 31
	s_lshl_b64 s[4:5], s[4:5], 18
	s_add_u32 s4, s1, s4
	s_addc_u32 s5, s3, s5
	s_and_b32 s19, s19, -4
	s_sub_i32 s90, s89, s19
	s_ashr_i32 s91, s90, 31
	s_lshl_b64 s[90:91], s[90:91], 19
	s_mov_b32 m0, s16
	v_mov_b32_e32 v85, v65
	s_add_u32 s90, s20, s90
	v_lshl_add_u64 v[86:87], s[4:5], 0, v[84:85]
	s_addc_u32 s91, s21, s91
	global_load_lds_dwordx4 v84, s[4:5]
	s_mov_b32 m0, s84
	v_lshl_add_u64 v[88:89], s[90:91], 0, v[84:85]
	global_load_lds_dwordx4 v84, s[90:91]
	v_lshl_add_u64 v[90:91], v[86:87], 0, s[38:39]
	s_mov_b32 m0, s85
	s_nop 0
	global_load_lds_dwordx4 v[90:91], off
	v_lshl_add_u64 v[90:91], v[88:89], 0, s[38:39]
	s_mov_b32 m0, s86
	s_nop 0
	global_load_lds_dwordx4 v[90:91], off
	v_lshl_add_u64 v[90:91], v[88:89], 0, s[42:43]
	s_mov_b32 m0, s87
	s_nop 0
	global_load_lds_dwordx4 v[90:91], off
	v_lshl_add_u64 v[90:91], v[88:89], 0, s[44:45]
	s_mov_b32 m0, s88
	s_nop 0
	global_load_lds_dwordx4 v[90:91], off

; #define MFMA(a, b, c) __builtin_amdgcn_mfma_f32_32x32x16_bf16((a), (b), (c), 0, 0, 0)
; #define G_BARRIER() { asm volatile("s_waitcnt vmcnt(0) lgkmcnt(0)" ::: "memory"); __builtin_amdgcn_s_barrier(); asm volatile("" ::: "memory"); }
;     ...
;         for (int kt = 0; kt < nk; ++kt) {
;             if (kt + 1 < nk) { G_DMA(kt + 1, (kt + 1) & 1); }
;             const unsigned char* sa = lds + (kt & 1) * 65536 + (wt * 32 * TB + r) * 128;
;             const unsigned char* sw = lds + (kt & 1) * 65536 + 32768 + (wf * 64 + r) * 128;
; #pragma unroll
;             for (int ks = 0; ks < 4; ++ks) {
;                 bf16x8 wfr[2], afr[TB];
; #pragma unroll
;                 for (int fb = 0; fb < 2; ++fb) wfr[fb] = *(const bf16x8*)(sw + fb * 4096 + koff[ks]);
; #pragma unroll
;                 for (int tb = 0; tb < TB; ++tb) afr[tb] = *(const bf16x8*)(sa + tb * 4096 + koff[ks]);
; #pragma unroll
;                 for (int fb = 0; fb < 2; ++fb)
; #pragma unroll
;                     for (int tb = 0; tb < TB; ++tb) acc[fb][tb] = MFMA(wfr[fb], afr[tb], acc[fb][tb]);
;             }
;             G_BARRIER();
;         }
.LBB0_743:
	s_add_i32 s8, s0, 0x10000
	s_and_b32 s9, s8, 0x10000
	s_add_i32 s9, s97, s9
	s_mov_b32 m0, s9
	s_nop 0
	global_load_lds_dwordx4 v240, s[56:57]
	s_add_i32 m0, s9, 0x8000
	s_nop 0
	global_load_lds_dwordx4 v240, s[58:59]
	s_add_i32 m0, s9, 0x2000
	s_nop 0
	global_load_lds_dwordx4 v241, s[56:57]
	s_add_i32 m0, s9, 0xa000
	s_nop 0
	global_load_lds_dwordx4 v241, s[58:59]
	s_add_i32 m0, s9, 0x4000
	s_nop 0
	global_load_lds_dwordx4 v242, s[56:57]
	s_add_i32 m0, s9, 0xc000
	s_nop 0
	global_load_lds_dwordx4 v242, s[58:59]
	s_add_i32 m0, s9, 0x6000
	s_nop 0
	global_load_lds_dwordx4 v243, s[56:57]
	s_add_i32 m0, s9, 0xe000
	s_and_b32 s0, s0, 0x10000
	s_nop 0
	global_load_lds_dwordx4 v243, s[58:59]
	s_add_u32 s56, s56, 0x80
	s_addc_u32 s57, s57, 0
	s_add_u32 s58, s58, 0x80
	s_addc_u32 s59, s59, 0
	s_add_i32 s0, s0, 16
	v_add3_u32 v132, s0, v181, v182
	v_add3_u32 v165, s0, v183, v182
	v_add_u32_e32 v191, v165, v176
	v_add_u32_e32 v200, v132, v176
	ds_read_b128 v[128:131], v191 offset:32768
	ds_read_b128 v[170:173], v200
	ds_read_b128 v[192:195], v191 offset:36864
	ds_read_b128 v[196:199], v200 offset:4096
	ds_read_b128 v[204:207], v200 offset:8192
	ds_read_b128 v[208:211], v200 offset:12288
	v_add_u32_e32 v174, v165, v177
	v_add_u32_e32 v175, v132, v177
	ds_read_b128 v[216:219], v174 offset:32768
	ds_read_b128 v[220:223], v175
	ds_read_b128 v[224:227], v174 offset:36864
	ds_read_b128 v[228:231], v175 offset:4096
	ds_read_b128 v[232:235], v175 offset:8192
	ds_read_b128 v[236:239], v175 offset:12288
	s_waitcnt lgkmcnt(6)
	v_mfma_f32_32x32x16_bf16 v[112:127], v[128:131], v[170:173], v[112:127]
	s_add_u32 s6, s6, 0x80
	s_addc_u32 s7, s7, 0
	s_cmpk_eq_i32 s6, 0x780
	s_mov_b32 s0, s8
	v_mfma_f32_32x32x16_bf16 v[96:111], v[128:131], v[196:199], v[96:111]
	v_mfma_f32_32x32x16_bf16 v[80:95], v[128:131], v[204:207], v[80:95]
	v_mfma_f32_32x32x16_bf16 v[64:79], v[128:131], v[208:211], v[64:79]
	v_mfma_f32_32x32x16_bf16 v[48:63], v[192:195], v[170:173], v[48:63]
	v_mfma_f32_32x32x16_bf16 v[32:47], v[192:195], v[196:199], v[32:47]
	v_mfma_f32_32x32x16_bf16 v[16:31], v[192:195], v[204:207], v[16:31]
	v_mfma_f32_32x32x16_bf16 v[0:15], v[192:195], v[208:211], v[0:15]
	v_add_u32_e32 v174, v165, v178
	v_add_u32_e32 v175, v132, v178
	ds_read_b128 v[128:131], v174 offset:32768
	ds_read_b128 v[170:173], v175
	ds_read_b128 v[192:195], v174 offset:36864
	ds_read_b128 v[196:199], v175 offset:4096
	ds_read_b128 v[204:207], v175 offset:8192
	ds_read_b128 v[208:211], v175 offset:12288
	s_waitcnt lgkmcnt(6)
	v_mfma_f32_32x32x16_bf16 v[112:127], v[216:219], v[220:223], v[112:127]
	v_mfma_f32_32x32x16_bf16 v[96:111], v[216:219], v[228:231], v[96:111]
	v_mfma_f32_32x32x16_bf16 v[80:95], v[216:219], v[232:235], v[80:95]
	v_mfma_f32_32x32x16_bf16 v[64:79], v[216:219], v[236:239], v[64:79]
	v_mfma_f32_32x32x16_bf16 v[48:63], v[224:227], v[220:223], v[48:63]
	v_mfma_f32_32x32x16_bf16 v[32:47], v[224:227], v[228:231], v[32:47]
	v_mfma_f32_32x32x16_bf16 v[16:31], v[224:227], v[232:235], v[16:31]
	v_mfma_f32_32x32x16_bf16 v[0:15], v[224:227], v[236:239], v[0:15]
	v_add_u32_e32 v165, v165, v179
	v_add_u32_e32 v132, v132, v179
	ds_read_b128 v[216:219], v165 offset:32768
	ds_read_b128 v[220:223], v132
	ds_read_b128 v[224:227], v165 offset:36864
	ds_read_b128 v[228:231], v132 offset:4096
	ds_read_b128 v[232:235], v132 offset:8192
	ds_read_b128 v[236:239], v132 offset:12288
	s_waitcnt lgkmcnt(6)
	v_mfma_f32_32x32x16_bf16 v[112:127], v[128:131], v[170:173], v[112:127]
	v_mfma_f32_32x32x16_bf16 v[96:111], v[128:131], v[196:199], v[96:111]
	v_mfma_f32_32x32x16_bf16 v[80:95], v[128:131], v[204:207], v[80:95]
	v_mfma_f32_32x32x16_bf16 v[64:79], v[128:131], v[208:211], v[64:79]
	v_mfma_f32_32x32x16_bf16 v[48:63], v[192:195], v[170:173], v[48:63]
	v_mfma_f32_32x32x16_bf16 v[32:47], v[192:195], v[196:199], v[32:47]
	v_mfma_f32_32x32x16_bf16 v[16:31], v[192:195], v[204:207], v[16:31]
	v_mfma_f32_32x32x16_bf16 v[0:15], v[192:195], v[208:211], v[0:15]
	s_waitcnt vmcnt(0) lgkmcnt(0)
	s_barrier
	v_mfma_f32_32x32x16_bf16 v[112:127], v[216:219], v[220:223], v[112:127]
	v_mfma_f32_32x32x16_bf16 v[96:111], v[216:219], v[228:231], v[96:111]
	v_mfma_f32_32x32x16_bf16 v[80:95], v[216:219], v[232:235], v[80:95]
	v_mfma_f32_32x32x16_bf16 v[64:79], v[216:219], v[236:239], v[64:79]
	v_mfma_f32_32x32x16_bf16 v[48:63], v[224:227], v[220:223], v[48:63]
	v_mfma_f32_32x32x16_bf16 v[32:47], v[224:227], v[228:231], v[32:47]
	v_mfma_f32_32x32x16_bf16 v[16:31], v[224:227], v[232:235], v[16:31]
	v_mfma_f32_32x32x16_bf16 v[0:15], v[224:227], v[236:239], v[0:15]
	s_cbranch_scc0 .LBB0_743
; #define GAS __attribute__((address_space(1)))
; #define MFMA(a, b, c) __builtin_amdgcn_mfma_f32_32x32x16_bf16((a), (b), (c), 0, 0, 0)
; #define G_BARRIER() { asm volatile("s_waitcnt vmcnt(0) lgkmcnt(0)" ::: "memory"); __builtin_amdgcn_s_barrier(); asm volatile("" ::: "memory"); }
;     ...
;         for (int kt = 0; kt < nk; ++kt) {
;             if (kt + 1 < nk) { G_DMA(kt + 1, (kt + 1) & 1); }
;             const unsigned char* sa = lds + (kt & 1) * 65536 + (wt * 32 * TB + r) * 128;
;             const unsigned char* sw = lds + (kt & 1) * 65536 + 32768 + (wf * 64 + r) * 128;
; #pragma unroll
;             for (int ks = 0; ks < 4; ++ks) {
;                 bf16x8 wfr[2], afr[TB];
; #pragma unroll
;                 for (int fb = 0; fb < 2; ++fb) wfr[fb] = *(const bf16x8*)(sw + fb * 4096 + koff[ks]);
; #pragma unroll
;                 for (int tb = 0; tb < TB; ++tb) afr[tb] = *(const bf16x8*)(sa + tb * 4096 + koff[ks]);
; #pragma unroll
;                 for (int fb = 0; fb < 2; ++fb)
; #pragma unroll
;                     for (int tb = 0; tb < TB; ++tb) acc[fb][tb] = MFMA(wfr[fb], afr[tb], acc[fb][tb]);
;             }
;             G_BARRIER();
;         }
;         const int un = u + nslots;
;         if (un < nloc) {
;             Ag = (const GAS bf16_t*)(A + (size_t)(xcd + nx * (un / Ntiles)) * RM * K) + dsrc; Wg = (const GAS bf16_t*)(Wt + (size_t)(un % Ntiles) * 256 * K) + dsrc;
;             G_DMA(0, 0);
;         }
	v_add_u32_e32 v132, v187, v176
	ds_read_b128 v[128:131], v132
	v_add_u32_e32 v165, v186, v176
	ds_read_b128 v[170:173], v165
	ds_read_b128 v[192:195], v165 offset:4096
	ds_read_b128 v[196:199], v165 offset:8192
	ds_read_b128 v[204:207], v165 offset:12288
	v_add_u32_e32 v165, v186, v177
	s_add_i32 s0, s1, s71
	s_cmp_ge_i32 s0, s72
	s_waitcnt lgkmcnt(0)
	v_mfma_f32_32x32x16_bf16 v[112:127], v[128:131], v[170:173], v[112:127]
	s_cselect_b64 s[60:61], -1, 0
	s_cmp_lt_i32 s0, s72
	v_mfma_f32_32x32x16_bf16 v[96:111], v[128:131], v[192:195], v[96:111]
	v_mfma_f32_32x32x16_bf16 v[80:95], v[128:131], v[196:199], v[80:95]
	v_mfma_f32_32x32x16_bf16 v[64:79], v[128:131], v[204:207], v[64:79]
	ds_read_b128 v[128:131], v132 offset:4096
	v_add_u32_e32 v132, v187, v177
	s_waitcnt lgkmcnt(0)
	v_mfma_f32_32x32x16_bf16 v[48:63], v[128:131], v[170:173], v[48:63]
	ds_read_b128 v[170:173], v165
	v_mfma_f32_32x32x16_bf16 v[32:47], v[128:131], v[192:195], v[32:47]
	ds_read_b128 v[192:195], v165 offset:4096
	v_mfma_f32_32x32x16_bf16 v[16:31], v[128:131], v[196:199], v[16:31]
	ds_read_b128 v[196:199], v165 offset:8192
	v_mfma_f32_32x32x16_bf16 v[0:15], v[128:131], v[204:207], v[0:15]
	ds_read_b128 v[128:131], v132
	ds_read_b128 v[204:207], v165 offset:12288
	v_add_u32_e32 v165, v186, v178
	s_waitcnt lgkmcnt(0)
	v_mfma_f32_32x32x16_bf16 v[112:127], v[128:131], v[170:173], v[112:127]
	v_mfma_f32_32x32x16_bf16 v[96:111], v[128:131], v[192:195], v[96:111]
	v_mfma_f32_32x32x16_bf16 v[80:95], v[128:131], v[196:199], v[80:95]
	v_mfma_f32_32x32x16_bf16 v[64:79], v[128:131], v[204:207], v[64:79]
	ds_read_b128 v[128:131], v132 offset:4096
	v_add_u32_e32 v132, v187, v178
	s_waitcnt lgkmcnt(0)
	v_mfma_f32_32x32x16_bf16 v[48:63], v[128:131], v[170:173], v[48:63]
	ds_read_b128 v[170:173], v165
	v_mfma_f32_32x32x16_bf16 v[32:47], v[128:131], v[192:195], v[32:47]
	ds_read_b128 v[192:195], v165 offset:4096
	v_mfma_f32_32x32x16_bf16 v[16:31], v[128:131], v[196:199], v[16:31]
	ds_read_b128 v[196:199], v165 offset:8192
	v_mfma_f32_32x32x16_bf16 v[0:15], v[128:131], v[204:207], v[0:15]
	ds_read_b128 v[128:131], v132
	ds_read_b128 v[204:207], v165 offset:12288
	v_add_u32_e32 v165, v186, v179
	s_waitcnt lgkmcnt(0)
	v_mfma_f32_32x32x16_bf16 v[112:127], v[128:131], v[170:173], v[112:127]
	v_mfma_f32_32x32x16_bf16 v[96:111], v[128:131], v[192:195], v[96:111]
	v_mfma_f32_32x32x16_bf16 v[80:95], v[128:131], v[196:199], v[80:95]
	v_mfma_f32_32x32x16_bf16 v[64:79], v[128:131], v[204:207], v[64:79]
	ds_read_b128 v[128:131], v132 offset:4096
	v_add_u32_e32 v132, v187, v179
	s_waitcnt lgkmcnt(0)
	v_mfma_f32_32x32x16_bf16 v[48:63], v[128:131], v[170:173], v[48:63]
	ds_read_b128 v[170:173], v165
	v_mfma_f32_32x32x16_bf16 v[32:47], v[128:131], v[192:195], v[32:47]
	ds_read_b128 v[192:195], v165 offset:4096
	v_mfma_f32_32x32x16_bf16 v[16:31], v[128:131], v[196:199], v[16:31]
	ds_read_b128 v[196:199], v165 offset:8192
	v_mfma_f32_32x32x16_bf16 v[0:15], v[128:131], v[204:207], v[0:15]
	ds_read_b128 v[128:131], v132
	ds_read_b128 v[204:207], v165 offset:12288
	s_waitcnt lgkmcnt(0)
	v_mfma_f32_32x32x16_bf16 v[112:127], v[128:131], v[170:173], v[112:127]
	v_mfma_f32_32x32x16_bf16 v[96:111], v[128:131], v[192:195], v[96:111]
	v_mfma_f32_32x32x16_bf16 v[80:95], v[128:131], v[196:199], v[80:95]
	v_mfma_f32_32x32x16_bf16 v[64:79], v[128:131], v[204:207], v[64:79]
	ds_read_b128 v[128:131], v132 offset:4096
	s_waitcnt vmcnt(0) lgkmcnt(0)
	s_barrier
	s_waitcnt lgkmcnt(0)
	v_mfma_f32_32x32x16_bf16 v[48:63], v[128:131], v[170:173], v[48:63]
	v_mfma_f32_32x32x16_bf16 v[32:47], v[128:131], v[192:195], v[32:47]
	v_mfma_f32_32x32x16_bf16 v[16:31], v[128:131], v[196:199], v[16:31]
	v_mfma_f32_32x32x16_bf16 v[0:15], v[128:131], v[204:207], v[0:15]
	s_cbranch_scc0 .LBB0_746
	s_mul_hi_i32 s6, s0, 0x2aaaaaab
	s_lshr_b32 s7, s6, 31
	s_add_i32 s8, s6, s7
	s_lshl_b32 s6, s8, s67
	s_add_i32 s6, s6, s70
	s_ashr_i32 s7, s6, 31
	s_lshl_b64 s[6:7], s[6:7], 19
	s_add_u32 s6, s38, s6
	s_mul_i32 s8, s8, 6
	s_addc_u32 s7, s39, s7
	s_sub_i32 s8, s0, s8
	s_ashr_i32 s9, s8, 31
	s_lshl_b64 s[8:9], s[8:9], 19
	s_mov_b32 m0, s97
	v_mov_b32_e32 v165, v133
	s_add_u32 s8, s40, s8
	v_lshl_add_u64 v[166:167], s[6:7], 0, v[164:165]
	s_addc_u32 s9, s41, s9
	global_load_lds_dwordx4 v164, s[6:7]
	s_add_i32 m0, s97, 0x8000
	v_lshl_add_u64 v[168:169], s[8:9], 0, v[164:165]
	global_load_lds_dwordx4 v164, s[8:9]
	v_lshl_add_u64 v[128:129], v[166:167], 0, s[44:45]
	s_add_i32 m0, s97, 0x2000
	s_nop 0
	global_load_lds_dwordx4 v[128:129], off
	v_lshl_add_u64 v[128:129], v[168:169], 0, s[44:45]
	s_add_i32 m0, s97, 0xa000
	s_nop 0
	global_load_lds_dwordx4 v[128:129], off
	v_lshl_add_u64 v[128:129], v[166:167], 0, s[46:47]
	s_add_i32 m0, s97, 0x4000
	s_nop 0
	global_load_lds_dwordx4 v[128:129], off
	v_lshl_add_u64 v[128:129], v[168:169], 0, s[46:47]
	s_add_i32 m0, s97, 0xc000
	s_nop 0
	global_load_lds_dwordx4 v[128:129], off
	v_lshl_add_u64 v[128:129], v[166:167], 0, s[48:49]
	s_add_i32 m0, s97, 0x6000
	s_nop 0
	global_load_lds_dwordx4 v[128:129], off
	v_lshl_add_u64 v[128:129], v[168:169], 0, s[48:49]
	s_add_i32 m0, s97, 0xe000
	s_nop 0
	global_load_lds_dwordx4 v[128:129], off
